# speedup vs baseline: 1.2051x; 1.0007x over previous
.LBB0_180:
	flat_load_dword v25, v[0:1] offset:1024 sc1
	flat_load_dword v10, v[0:1] offset:1280 sc1
	flat_load_dword v11, v[0:1] offset:1536 sc1
	flat_load_dword v12, v[0:1] offset:1792 sc1
	flat_load_dword v13, v[0:1] offset:2048 sc1
	flat_load_dword v14, v[0:1] offset:2304 sc1
	flat_load_dword v15, v[0:1] offset:2560 sc1
	flat_load_dword v16, v[0:1] offset:2816 sc1
	flat_load_dword v17, v[0:1] offset:3072 sc1
	flat_load_dword v18, v[0:1] offset:3328 sc1
	flat_load_dword v19, v[0:1] offset:3584 sc1
	flat_load_dword v20, v[0:1] offset:3840 sc1
	flat_load_dword v21, v[2:3] sc1
	flat_load_dword v22, v[4:5] sc1
	flat_load_dword v23, v[6:7] sc1
	flat_load_dword v24, v[8:9] sc1
	s_or_b64 s[12:13], s[12:13], exec
	s_or_b64 s[10:11], s[10:11], exec
	s_waitcnt vmcnt(0) lgkmcnt(0)
	v_add_u32_e32 v26, v10, v25
	v_add_u32_e32 v26, v26, v11
	v_add_u32_e32 v26, v26, v12
	v_add_u32_e32 v26, v26, v13
	v_add_u32_e32 v26, v26, v14
	v_add_u32_e32 v26, v26, v15
	v_add_u32_e32 v26, v26, v16
	v_add_u32_e32 v26, v26, v17
	v_add_u32_e32 v26, v26, v18
	v_add_u32_e32 v26, v26, v19
	v_add_u32_e32 v26, v26, v20
	v_add_u32_e32 v26, v26, v21
	v_add_u32_e32 v26, v26, v22
	v_add_u32_e32 v26, v26, v23
	v_add_u32_e32 v26, v26, v24
	v_cmp_ne_u32_e32 vcc, s33, v26
	s_and_saveexec_b64 s[14:15], vcc
	s_cbranch_execz .LBB0_179
	s_and_b32 s18, s3, 0xff
	s_mov_b64 s[16:17], -1
	s_cmp_eq_u32 s18, 0
	s_mov_b64 s[20:21], -1
	s_mov_b64 s[18:19], -1
	s_sleep 4
	s_cbranch_scc1 .LBB0_183
	s_and_saveexec_b64 s[22:23], s[20:21]
	s_cbranch_execz .LBB0_178
	s_branch .LBB0_186

.LBB0_194:
	s_and_b32 s20, s26, 0xff
	s_mov_b64 s[18:19], -1
	s_cmp_lg_u32 s20, 0
	s_mov_b64 s[20:21], -1
	s_sleep 4
	s_cbranch_scc1 .LBB0_198
	v_mov_b64_e32 v[0:1], s[40:41]
	flat_load_dword v0, v[0:1] offset:512 sc1
	s_mov_b64 s[20:21], 0
	s_mov_b64 s[22:23], -1
	s_waitcnt vmcnt(0) lgkmcnt(0)
	v_cmp_eq_u32_e32 vcc, 0, v0
	s_and_saveexec_b64 s[24:25], vcc
	s_cmp_lt_u32 s26, 0x40001
	s_cselect_b64 s[20:21], -1, 0
	s_xor_b64 s[22:23], exec, -1
	s_and_b64 s[20:21], s[20:21], exec
	s_or_b64 exec, exec, s[24:25]

.LBB0_208:
	s_and_b32 s20, s28, 0xff
	s_cmp_lg_u32 s20, 0
	s_mov_b64 s[22:23], -1
	s_sleep 4
	s_cbranch_scc0 .LBB0_210
	s_mov_b64 s[24:25], -1
	s_and_saveexec_b64 s[26:27], s[22:23]
	s_cbranch_execz .LBB0_207
	s_branch .LBB0_213

.LBB0_342:
	flat_load_dword v25, v[0:1] offset:1024 sc1
	flat_load_dword v10, v[0:1] offset:1280 sc1
	flat_load_dword v11, v[0:1] offset:1536 sc1
	flat_load_dword v12, v[0:1] offset:1792 sc1
	flat_load_dword v13, v[0:1] offset:2048 sc1
	flat_load_dword v14, v[0:1] offset:2304 sc1
	flat_load_dword v15, v[0:1] offset:2560 sc1
	flat_load_dword v16, v[0:1] offset:2816 sc1
	flat_load_dword v17, v[0:1] offset:3072 sc1
	flat_load_dword v18, v[0:1] offset:3328 sc1
	flat_load_dword v19, v[0:1] offset:3584 sc1
	flat_load_dword v20, v[0:1] offset:3840 sc1
	flat_load_dword v21, v[2:3] sc1
	flat_load_dword v22, v[4:5] sc1
	flat_load_dword v23, v[6:7] sc1
	flat_load_dword v24, v[8:9] sc1
	s_or_b64 s[10:11], s[10:11], exec
	s_or_b64 s[8:9], s[8:9], exec
	s_waitcnt vmcnt(0) lgkmcnt(0)
	v_add_u32_e32 v26, v10, v25
	v_add_u32_e32 v26, v26, v11
	v_add_u32_e32 v26, v26, v12
	v_add_u32_e32 v26, v26, v13
	v_add_u32_e32 v26, v26, v14
	v_add_u32_e32 v26, v26, v15
	v_add_u32_e32 v26, v26, v16
	v_add_u32_e32 v26, v26, v17
	v_add_u32_e32 v26, v26, v18
	v_add_u32_e32 v26, v26, v19
	v_add_u32_e32 v26, v26, v20
	v_add_u32_e32 v26, v26, v21
	v_add_u32_e32 v26, v26, v22
	v_add_u32_e32 v26, v26, v23
	v_add_u32_e32 v26, v26, v24
	v_cmp_ne_u32_e32 vcc, s33, v26
	s_and_saveexec_b64 s[12:13], vcc
	s_cbranch_execz .LBB0_341
	s_and_b32 s16, s3, 0xff
	s_mov_b64 s[14:15], -1
	s_cmp_eq_u32 s16, 0
	s_mov_b64 s[18:19], -1
	s_mov_b64 s[16:17], -1
	s_sleep 4
	s_cbranch_scc1 .LBB0_345
	s_and_saveexec_b64 s[20:21], s[18:19]
	s_cbranch_execz .LBB0_340
	s_branch .LBB0_348

.LBB0_356:
	s_and_b32 s18, s24, 0xff
	s_mov_b64 s[16:17], -1
	s_cmp_lg_u32 s18, 0
	s_mov_b64 s[18:19], -1
	s_sleep 4
	s_cbranch_scc1 .LBB0_360
	v_mov_b64_e32 v[0:1], s[38:39]
	flat_load_dword v0, v[0:1] offset:512 sc1
	s_mov_b64 s[18:19], 0
	s_mov_b64 s[20:21], -1
	s_waitcnt vmcnt(0) lgkmcnt(0)
	v_cmp_eq_u32_e32 vcc, 0, v0
	s_and_saveexec_b64 s[22:23], vcc
	s_cmp_lt_u32 s24, 0x40001
	s_cselect_b64 s[18:19], -1, 0
	s_xor_b64 s[20:21], exec, -1
	s_and_b64 s[18:19], s[18:19], exec
	s_or_b64 exec, exec, s[22:23]

.LBB0_370:
	s_and_b32 s16, s24, 0xff
	s_cmp_lg_u32 s16, 0
	s_mov_b64 s[18:19], -1
	s_sleep 4
	s_cbranch_scc0 .LBB0_372
	s_mov_b64 s[20:21], -1
	s_and_saveexec_b64 s[22:23], s[18:19]
	s_cbranch_execz .LBB0_369
	s_branch .LBB0_375

.LBB0_822:
	v_mov_b64_e32 v[12:13], s[96:97]
	flat_load_dword v2, v[12:13] offset:1024 sc1
	flat_load_dword v0, v[12:13] offset:1280 sc1
	flat_load_dword v3, v[12:13] offset:1536 sc1
	s_or_b64 s[20:21], s[20:21], exec
	s_or_b64 s[18:19], s[18:19], exec
	s_waitcnt vmcnt(0) lgkmcnt(0)
	v_add_u32_e32 v4, v0, v2
	v_add_u32_e32 v5, v4, v3
	flat_load_dword v4, v[12:13] offset:1792 sc1
	s_waitcnt vmcnt(0) lgkmcnt(0)
	v_add_u32_e32 v6, v5, v4
	flat_load_dword v5, v[12:13] offset:2048 sc1
	s_waitcnt vmcnt(0) lgkmcnt(0)
	v_add_u32_e32 v7, v6, v5
	flat_load_dword v6, v[12:13] offset:2304 sc1
	s_waitcnt vmcnt(0) lgkmcnt(0)
	v_add_u32_e32 v8, v7, v6
	flat_load_dword v7, v[12:13] offset:2560 sc1
	s_waitcnt vmcnt(0) lgkmcnt(0)
	v_add_u32_e32 v9, v8, v7
	flat_load_dword v8, v[12:13] offset:2816 sc1
	s_waitcnt vmcnt(0) lgkmcnt(0)
	v_add_u32_e32 v10, v9, v8
	flat_load_dword v9, v[12:13] offset:3072 sc1
	s_waitcnt vmcnt(0) lgkmcnt(0)
	v_add_u32_e32 v11, v10, v9
	flat_load_dword v10, v[12:13] offset:3328 sc1
	s_waitcnt vmcnt(0) lgkmcnt(0)
	v_add_u32_e32 v14, v11, v10
	flat_load_dword v11, v[12:13] offset:3584 sc1
	s_waitcnt vmcnt(0) lgkmcnt(0)
	v_add_u32_e32 v14, v14, v11
	flat_load_dword v12, v[12:13] offset:3840 sc1
	s_waitcnt vmcnt(0) lgkmcnt(0)
	v_add_u32_e32 v16, v14, v12
	v_mov_b64_e32 v[14:15], s[6:7]
	flat_load_dword v13, v[14:15] sc1
	v_mov_b64_e32 v[14:15], s[8:9]
	flat_load_dword v14, v[14:15] sc1
	s_waitcnt vmcnt(0) lgkmcnt(0)
	v_add_u32_e32 v16, v16, v13
	v_add_u32_e32 v18, v16, v14
	v_mov_b64_e32 v[16:17], s[10:11]
	flat_load_dword v15, v[16:17] sc1
	v_mov_b64_e32 v[16:17], s[12:13]
	flat_load_dword v16, v[16:17] sc1
	s_waitcnt vmcnt(0) lgkmcnt(0)
	v_add_u32_e32 v18, v18, v15
	v_add_u32_e32 v17, v18, v16
	v_cmp_ne_u32_e32 vcc, s33, v17
	s_and_saveexec_b64 s[22:23], vcc
	s_cbranch_execz .LBB0_821
	s_and_b32 s4, s3, 0xff
	s_mov_b64 s[24:25], -1
	s_cmp_eq_u32 s4, 0
	s_mov_b64 s[28:29], -1
	s_mov_b64 s[26:27], -1
	s_sleep 4
	s_cbranch_scc1 .LBB0_825
	s_and_saveexec_b64 s[30:31], s[28:29]
	s_cbranch_execz .LBB0_820
	s_branch .LBB0_828

.LBB0_836:
	s_and_b32 s5, s4, 0xff
	s_mov_b64 s[18:19], -1
	s_cmp_lg_u32 s5, 0
	s_mov_b64 s[20:21], -1
	s_sleep 4
	s_cbranch_scc1 .LBB0_840
	v_mov_b64_e32 v[2:3], s[96:97]
	flat_load_dword v2, v[2:3] offset:512 sc1
	s_mov_b64 s[20:21], 0
	s_mov_b64 s[22:23], -1
	s_waitcnt vmcnt(0) lgkmcnt(0)
	v_cmp_eq_u32_e32 vcc, 0, v2
	s_and_saveexec_b64 s[24:25], vcc
	s_cmp_lt_u32 s4, 0x40001
	s_cselect_b64 s[20:21], -1, 0
	s_xor_b64 s[22:23], exec, -1
	s_and_b64 s[20:21], s[20:21], exec
	s_or_b64 exec, exec, s[24:25]

.LBB0_850:
	s_and_b32 s5, s4, 0xff
	s_mov_b64 s[18:19], -1
	s_cmp_lg_u32 s5, 0
	s_mov_b64 s[22:23], -1
	s_sleep 4
	s_cbranch_scc0 .LBB0_852
	s_and_saveexec_b64 s[24:25], s[22:23]
	s_cbranch_execz .LBB0_849
	s_branch .LBB0_855

.LBB0_1382:
	v_mov_b64_e32 v[12:13], s[68:69]
	flat_load_dword v2, v[12:13] offset:1024 sc1
	flat_load_dword v0, v[12:13] offset:1280 sc1
	flat_load_dword v3, v[12:13] offset:1536 sc1
	s_or_b64 s[20:21], s[20:21], exec
	s_or_b64 s[18:19], s[18:19], exec
	s_waitcnt vmcnt(0) lgkmcnt(0)
	v_add_u32_e32 v4, v0, v2
	v_add_u32_e32 v5, v4, v3
	flat_load_dword v4, v[12:13] offset:1792 sc1
	s_waitcnt vmcnt(0) lgkmcnt(0)
	v_add_u32_e32 v6, v5, v4
	flat_load_dword v5, v[12:13] offset:2048 sc1
	s_waitcnt vmcnt(0) lgkmcnt(0)
	v_add_u32_e32 v7, v6, v5
	flat_load_dword v6, v[12:13] offset:2304 sc1
	s_waitcnt vmcnt(0) lgkmcnt(0)
	v_add_u32_e32 v8, v7, v6
	flat_load_dword v7, v[12:13] offset:2560 sc1
	s_waitcnt vmcnt(0) lgkmcnt(0)
	v_add_u32_e32 v9, v8, v7
	flat_load_dword v8, v[12:13] offset:2816 sc1
	s_waitcnt vmcnt(0) lgkmcnt(0)
	v_add_u32_e32 v10, v9, v8
	flat_load_dword v9, v[12:13] offset:3072 sc1
	s_waitcnt vmcnt(0) lgkmcnt(0)
	v_add_u32_e32 v11, v10, v9
	flat_load_dword v10, v[12:13] offset:3328 sc1
	s_waitcnt vmcnt(0) lgkmcnt(0)
	v_add_u32_e32 v14, v11, v10
	flat_load_dword v11, v[12:13] offset:3584 sc1
	s_waitcnt vmcnt(0) lgkmcnt(0)
	v_add_u32_e32 v14, v14, v11
	flat_load_dword v12, v[12:13] offset:3840 sc1
	s_waitcnt vmcnt(0) lgkmcnt(0)
	v_add_u32_e32 v16, v14, v12
	v_mov_b64_e32 v[14:15], s[6:7]
	flat_load_dword v13, v[14:15] sc1
	v_mov_b64_e32 v[14:15], s[8:9]
	flat_load_dword v14, v[14:15] sc1
	s_waitcnt vmcnt(0) lgkmcnt(0)
	v_add_u32_e32 v16, v16, v13
	v_add_u32_e32 v18, v16, v14
	v_mov_b64_e32 v[16:17], s[10:11]
	flat_load_dword v15, v[16:17] sc1
	v_mov_b64_e32 v[16:17], s[12:13]
	flat_load_dword v16, v[16:17] sc1
	s_waitcnt vmcnt(0) lgkmcnt(0)
	v_add_u32_e32 v18, v18, v15
	v_add_u32_e32 v17, v18, v16
	v_cmp_ne_u32_e32 vcc, s33, v17
	s_and_saveexec_b64 s[22:23], vcc
	s_cbranch_execz .LBB0_1381
	s_and_b32 s4, s3, 0xff
	s_mov_b64 s[24:25], -1
	s_cmp_eq_u32 s4, 0
	s_mov_b64 s[28:29], -1
	s_mov_b64 s[26:27], -1
	s_sleep 4
	s_cbranch_scc1 .LBB0_1385
	s_and_saveexec_b64 s[30:31], s[28:29]
	s_cbranch_execz .LBB0_1380
	s_branch .LBB0_1388

.LBB0_1396:
	s_and_b32 s5, s4, 0xff
	s_mov_b64 s[18:19], -1
	s_cmp_lg_u32 s5, 0
	s_mov_b64 s[20:21], -1
	s_sleep 4
	s_cbranch_scc1 .LBB0_1400
	v_mov_b64_e32 v[2:3], s[68:69]
	flat_load_dword v2, v[2:3] offset:512 sc1
	s_mov_b64 s[20:21], 0
	s_mov_b64 s[22:23], -1
	s_waitcnt vmcnt(0) lgkmcnt(0)
	v_cmp_eq_u32_e32 vcc, 0, v2
	s_and_saveexec_b64 s[24:25], vcc
	s_cmp_lt_u32 s4, 0x40001
	s_cselect_b64 s[20:21], -1, 0
	s_xor_b64 s[22:23], exec, -1
	s_and_b64 s[20:21], s[20:21], exec
	s_or_b64 exec, exec, s[24:25]

.LBB0_1452:
	v_mov_b64_e32 v[12:13], s[38:39]
	flat_load_dword v2, v[12:13] offset:1024 sc1
	flat_load_dword v0, v[12:13] offset:1280 sc1
	flat_load_dword v3, v[12:13] offset:1536 sc1
	s_or_b64 s[18:19], s[18:19], exec
	s_or_b64 s[16:17], s[16:17], exec
	s_waitcnt vmcnt(0) lgkmcnt(0)
	v_add_u32_e32 v4, v0, v2
	v_add_u32_e32 v5, v4, v3
	flat_load_dword v4, v[12:13] offset:1792 sc1
	s_waitcnt vmcnt(0) lgkmcnt(0)
	v_add_u32_e32 v6, v5, v4
	flat_load_dword v5, v[12:13] offset:2048 sc1
	s_waitcnt vmcnt(0) lgkmcnt(0)
	v_add_u32_e32 v7, v6, v5
	flat_load_dword v6, v[12:13] offset:2304 sc1
	s_waitcnt vmcnt(0) lgkmcnt(0)
	v_add_u32_e32 v8, v7, v6
	flat_load_dword v7, v[12:13] offset:2560 sc1
	s_waitcnt vmcnt(0) lgkmcnt(0)
	v_add_u32_e32 v9, v8, v7
	flat_load_dword v8, v[12:13] offset:2816 sc1
	s_waitcnt vmcnt(0) lgkmcnt(0)
	v_add_u32_e32 v10, v9, v8
	flat_load_dword v9, v[12:13] offset:3072 sc1
	s_waitcnt vmcnt(0) lgkmcnt(0)
	v_add_u32_e32 v11, v10, v9
	flat_load_dword v10, v[12:13] offset:3328 sc1
	s_waitcnt vmcnt(0) lgkmcnt(0)
	v_add_u32_e32 v14, v11, v10
	flat_load_dword v11, v[12:13] offset:3584 sc1
	s_waitcnt vmcnt(0) lgkmcnt(0)
	v_add_u32_e32 v14, v14, v11
	flat_load_dword v12, v[12:13] offset:3840 sc1
	s_waitcnt vmcnt(0) lgkmcnt(0)
	v_add_u32_e32 v16, v14, v12
	v_mov_b64_e32 v[14:15], s[4:5]
	flat_load_dword v13, v[14:15] sc1
	v_mov_b64_e32 v[14:15], s[6:7]
	flat_load_dword v14, v[14:15] sc1
	s_waitcnt vmcnt(0) lgkmcnt(0)
	v_add_u32_e32 v16, v16, v13
	v_add_u32_e32 v18, v16, v14
	v_mov_b64_e32 v[16:17], s[8:9]
	flat_load_dword v15, v[16:17] sc1
	v_mov_b64_e32 v[16:17], s[10:11]
	flat_load_dword v16, v[16:17] sc1
	s_waitcnt vmcnt(0) lgkmcnt(0)
	v_add_u32_e32 v18, v18, v15
	v_add_u32_e32 v17, v18, v16
	v_cmp_ne_u32_e32 vcc, s33, v17
	s_and_saveexec_b64 s[20:21], vcc
	s_cbranch_execz .LBB0_1451
	s_and_b32 s24, s3, 0xff
	s_mov_b64 s[22:23], -1
	s_cmp_eq_u32 s24, 0
	s_mov_b64 s[26:27], -1
	s_mov_b64 s[24:25], -1
	s_sleep 4
	s_cbranch_scc1 .LBB0_1455
	s_and_saveexec_b64 s[28:29], s[26:27]
	s_cbranch_execz .LBB0_1450
	s_branch .LBB0_1458

.LBB0_1466:
	s_and_b32 s18, s24, 0xff
	s_mov_b64 s[16:17], -1
	s_cmp_lg_u32 s18, 0
	s_mov_b64 s[18:19], -1
	s_sleep 4
	s_cbranch_scc1 .LBB0_1470
	v_mov_b64_e32 v[2:3], s[38:39]
	flat_load_dword v2, v[2:3] offset:512 sc1
	s_mov_b64 s[18:19], 0
	s_mov_b64 s[20:21], -1
	s_waitcnt vmcnt(0) lgkmcnt(0)
	v_cmp_eq_u32_e32 vcc, 0, v2
	s_and_saveexec_b64 s[22:23], vcc
	s_cmp_lt_u32 s24, 0x40001
	s_cselect_b64 s[18:19], -1, 0
	s_xor_b64 s[20:21], exec, -1
	s_and_b64 s[18:19], s[18:19], exec
	s_or_b64 exec, exec, s[22:23]

.LBB0_1480:
	s_and_b32 s18, s24, 0xff
	s_mov_b64 s[16:17], -1
	s_cmp_lg_u32 s18, 0
	s_mov_b64 s[20:21], -1
	s_sleep 4
	s_cbranch_scc0 .LBB0_1482
	s_and_saveexec_b64 s[22:23], s[20:21]
	s_cbranch_execz .LBB0_1479
	s_branch .LBB0_1485
